# mini GEMM tiles with 11 k-steps in flight instead of 8 (vmcnt(30) steady state), on top of v025
# baseline (speedup 1.0000x reference)
; DEVI f32x4 mfma16(bf16x8 a, bf16x8 b, f32x4 c) { return __builtin_amdgcn_mfma_f32_16x16x32_bf16(a, b, c, 0, 0, 0); }
; DEVI void mini_kloop(const bf16_t* __restrict__ arow, const bf16_t* __restrict__ b0, const bf16_t* __restrict__ b1, const int K, f32x4 (&acc)[2]) {
; #pragma unroll 8
;     for (int k0 = 0; k0 < K; k0 += 32) {
;         const bf16x8 af = *(const bf16x8*)(arow + k0), w0 = *(const bf16x8*)(b0 + k0), w1 = *(const bf16x8*)(b1 + k0);
;         acc[0] = mfma16(w0, af, acc[0]); acc[1] = mfma16(w1, af, acc[1]);
;     }
; }
; DEVI void mini_mix_tile(const Params& p, const int t) {
;     int tid = threadIdx.x; asm volatile("" : "+v"(tid));
;     const int lane = tid & 63, w = tid >> 6, l15 = lane & 15, g = lane >> 4;
;     const int tok = NTP + 64 * (t >> 4) + 16 * (w & 3) + l15, colw = 64 * (t & 15) + 32 * (w >> 2);
;     const bf16_t* OA = (const bf16_t*)(p.ws + W_OAB); const bf16_t* OB = OA + (size_t)NTOK * 512;
;     const bf16_t* WAT = (const bf16_t*)(p.ws + W_WABT); const bf16_t* WBT = WAT + 1024 * 512;
;     f32x4 aa[2] = {(f32x4){0.f, 0.f, 0.f, 0.f}, (f32x4){0.f, 0.f, 0.f, 0.f}}, ab[2] = {(f32x4){0.f, 0.f, 0.f, 0.f}, (f32x4){0.f, 0.f, 0.f, 0.f}};
;     mini_kloop(OA + (size_t)tok * 512 + 8 * g, WAT + (size_t)(colw + l15) * 512 + 8 * g, WAT + (size_t)(colw + 16 + l15) * 512 + 8 * g, 512, aa);
;     mini_kloop(OB + (size_t)tok * 512 + 8 * g, WBT + (size_t)(colw + l15) * 512 + 8 * g, WBT + (size_t)(colw + 16 + l15) * 512 + 8 * g, 512, ab);
.LBB0_995:
	v_mov_b32_e32 v8, 0
	v_mov_b32_e32 v9, 0
	v_mov_b32_e32 v10, 0
	v_mov_b32_e32 v11, 0
	v_mov_b32_e32 v12, 0
	v_mov_b32_e32 v13, 0
	v_mov_b32_e32 v14, 0
	v_mov_b32_e32 v15, 0
	v_lshl_add_u64 v[28:29], v[18:19], 0, v[16:17]
	v_lshl_add_u64 v[30:31], v[20:21], 0, v[16:17]
	v_lshl_add_u64 v[32:33], v[22:23], 0, v[16:17]
	v_add_co_u32_e32 v34, vcc, 0x1af48000, v28
	s_nop 1
	v_addc_co_u32_e32 v35, vcc, 0, v29, vcc
	v_add_co_u32_e32 v28, vcc, 0x18e48000, v28
	s_nop 1
	v_addc_co_u32_e32 v29, vcc, 0, v29, vcc
	v_add_co_u32_e32 v36, vcc, 0x5080000, v30
	s_nop 1
	v_addc_co_u32_e32 v37, vcc, 0, v31, vcc
	v_add_co_u32_e32 v30, vcc, 0x4f80000, v30
	s_nop 1
	v_addc_co_u32_e32 v31, vcc, 0, v31, vcc
	v_add_co_u32_e32 v38, vcc, 0x5080000, v32
	s_nop 1
	v_addc_co_u32_e32 v39, vcc, 0, v33, vcc
	v_add_co_u32_e32 v32, vcc, 0x4f80000, v32
	s_nop 1
	v_addc_co_u32_e32 v33, vcc, 0, v33, vcc
	v_and_b32_e32 v40, 63, v203
	v_and_b32_e32 v41, 3, v40
	v_lshrrev_b32_e32 v42, 4, v40
	v_bfe_u32 v43, v40, 2, 2
	v_lshl_add_u32 v44, v42, 2, v43
	v_lshl_add_u32 v44, v41, 4, v44
	v_lshlrev_b32_e32 v44, 2, v44
	v_lshlrev_b32_e32 v45, 4, v43
	v_lshl_add_u32 v45, v41, 2, v45
	v_add_u32_e32 v45, v45, v42
	v_lshlrev_b32_e32 v45, 2, v45
	ds_bpermute_b32 v28, v44, v28
	ds_bpermute_b32 v29, v44, v29
	ds_bpermute_b32 v30, v44, v30
	ds_bpermute_b32 v31, v44, v31
	ds_bpermute_b32 v32, v44, v32
	ds_bpermute_b32 v33, v44, v33
	ds_bpermute_b32 v34, v44, v34
	ds_bpermute_b32 v35, v44, v35
	ds_bpermute_b32 v36, v44, v36
	ds_bpermute_b32 v37, v44, v37
	ds_bpermute_b32 v38, v44, v38
	ds_bpermute_b32 v39, v44, v39
	s_waitcnt lgkmcnt(0)
	global_load_dwordx4 v[64:67], v[28:29], off
	global_load_dwordx4 v[68:71], v[30:31], off
	global_load_dwordx4 v[72:75], v[32:33], off
	global_load_dwordx4 v[76:79], v[28:29], off offset:64
	global_load_dwordx4 v[80:83], v[30:31], off offset:64
	global_load_dwordx4 v[84:87], v[32:33], off offset:64
	global_load_dwordx4 v[88:91], v[28:29], off offset:128
	global_load_dwordx4 v[92:95], v[30:31], off offset:128
	global_load_dwordx4 v[96:99], v[32:33], off offset:128
	global_load_dwordx4 v[100:103], v[28:29], off offset:192
	global_load_dwordx4 v[104:107], v[30:31], off offset:192
	global_load_dwordx4 v[108:111], v[32:33], off offset:192
	global_load_dwordx4 v[112:115], v[28:29], off offset:256
	global_load_dwordx4 v[116:119], v[30:31], off offset:256
	global_load_dwordx4 v[120:123], v[32:33], off offset:256
	global_load_dwordx4 v[124:127], v[28:29], off offset:320
	global_load_dwordx4 v[128:131], v[30:31], off offset:320
	global_load_dwordx4 v[132:135], v[32:33], off offset:320
	global_load_dwordx4 v[136:139], v[28:29], off offset:384
	global_load_dwordx4 v[140:143], v[30:31], off offset:384
	global_load_dwordx4 v[144:147], v[32:33], off offset:384
	global_load_dwordx4 v[148:151], v[28:29], off offset:448
	global_load_dwordx4 v[152:155], v[30:31], off offset:448
	global_load_dwordx4 v[156:159], v[32:33], off offset:448
	global_load_dwordx4 v[160:163], v[28:29], off offset:512
	global_load_dwordx4 v[164:167], v[30:31], off offset:512
	global_load_dwordx4 v[168:171], v[32:33], off offset:512
	global_load_dwordx4 v[172:175], v[28:29], off offset:576
	global_load_dwordx4 v[176:179], v[30:31], off offset:576
	global_load_dwordx4 v[180:183], v[32:33], off offset:576
	global_load_dwordx4 v[184:187], v[28:29], off offset:640
	global_load_dwordx4 v[188:191], v[30:31], off offset:640
	global_load_dwordx4 v[192:195], v[32:33], off offset:640
	s_waitcnt vmcnt(30)
	ds_bpermute_b32 v204, v45, v64
	ds_bpermute_b32 v205, v45, v65
	ds_bpermute_b32 v206, v45, v66
	ds_bpermute_b32 v207, v45, v67
	ds_bpermute_b32 v208, v45, v68
	ds_bpermute_b32 v209, v45, v69
	ds_bpermute_b32 v210, v45, v70
	ds_bpermute_b32 v211, v45, v71
	ds_bpermute_b32 v212, v45, v72
	ds_bpermute_b32 v213, v45, v73
	ds_bpermute_b32 v214, v45, v74
	ds_bpermute_b32 v215, v45, v75
	s_waitcnt vmcnt(27)
	s_waitcnt lgkmcnt(3)
	ds_bpermute_b32 v216, v45, v76
	ds_bpermute_b32 v217, v45, v77
	ds_bpermute_b32 v218, v45, v78
	ds_bpermute_b32 v219, v45, v79
	ds_bpermute_b32 v220, v45, v80
	ds_bpermute_b32 v221, v45, v81
	ds_bpermute_b32 v222, v45, v82
	ds_bpermute_b32 v223, v45, v83
	ds_bpermute_b32 v224, v45, v84
	ds_bpermute_b32 v225, v45, v85
	ds_bpermute_b32 v226, v45, v86
	ds_bpermute_b32 v227, v45, v87
	s_waitcnt lgkmcnt(12)
	v_mfma_f32_16x16x32_bf16 v[4:7], v[208:211], v[204:207], v[4:7]
	v_mfma_f32_16x16x32_bf16 v[0:3], v[212:215], v[204:207], v[0:3]
	global_load_dwordx4 v[64:67], v[28:29], off offset:704
	global_load_dwordx4 v[68:71], v[30:31], off offset:704
	global_load_dwordx4 v[72:75], v[32:33], off offset:704
	s_waitcnt vmcnt(27)
	s_waitcnt lgkmcnt(3)
	ds_bpermute_b32 v204, v45, v88
	ds_bpermute_b32 v205, v45, v89
	ds_bpermute_b32 v206, v45, v90
	ds_bpermute_b32 v207, v45, v91
	ds_bpermute_b32 v208, v45, v92
	ds_bpermute_b32 v209, v45, v93
	ds_bpermute_b32 v210, v45, v94
	ds_bpermute_b32 v211, v45, v95
	ds_bpermute_b32 v212, v45, v96
	ds_bpermute_b32 v213, v45, v97
	ds_bpermute_b32 v214, v45, v98
	ds_bpermute_b32 v215, v45, v99
	s_waitcnt lgkmcnt(12)
	v_mfma_f32_16x16x32_bf16 v[4:7], v[220:223], v[216:219], v[4:7]
	v_mfma_f32_16x16x32_bf16 v[0:3], v[224:227], v[216:219], v[0:3]
	global_load_dwordx4 v[76:79], v[28:29], off offset:768
	global_load_dwordx4 v[80:83], v[30:31], off offset:768
	global_load_dwordx4 v[84:87], v[32:33], off offset:768
	s_waitcnt vmcnt(27)
	s_waitcnt lgkmcnt(3)
	ds_bpermute_b32 v216, v45, v100
	ds_bpermute_b32 v217, v45, v101
	ds_bpermute_b32 v218, v45, v102
	ds_bpermute_b32 v219, v45, v103
	ds_bpermute_b32 v220, v45, v104
	ds_bpermute_b32 v221, v45, v105
	ds_bpermute_b32 v222, v45, v106
	ds_bpermute_b32 v223, v45, v107
	ds_bpermute_b32 v224, v45, v108
	ds_bpermute_b32 v225, v45, v109
	ds_bpermute_b32 v226, v45, v110
	ds_bpermute_b32 v227, v45, v111
	s_waitcnt lgkmcnt(12)
; DEVI f32x4 mfma16(bf16x8 a, bf16x8 b, f32x4 c) { return __builtin_amdgcn_mfma_f32_16x16x32_bf16(a, b, c, 0, 0, 0); }
; DEVI void mini_kloop(const bf16_t* __restrict__ arow, const bf16_t* __restrict__ b0, const bf16_t* __restrict__ b1, const int K, f32x4 (&acc)[2]) {
; #pragma unroll 8
;     for (int k0 = 0; k0 < K; k0 += 32) {
;         const bf16x8 af = *(const bf16x8*)(arow + k0), w0 = *(const bf16x8*)(b0 + k0), w1 = *(const bf16x8*)(b1 + k0);
;         acc[0] = mfma16(w0, af, acc[0]); acc[1] = mfma16(w1, af, acc[1]);
;     }
; }
	v_mfma_f32_16x16x32_bf16 v[4:7], v[208:211], v[204:207], v[4:7]
	v_mfma_f32_16x16x32_bf16 v[0:3], v[212:215], v[204:207], v[0:3]
	global_load_dwordx4 v[88:91], v[28:29], off offset:832
	global_load_dwordx4 v[92:95], v[30:31], off offset:832
	global_load_dwordx4 v[96:99], v[32:33], off offset:832
	s_waitcnt vmcnt(27)
	s_waitcnt lgkmcnt(3)
	ds_bpermute_b32 v204, v45, v112
	ds_bpermute_b32 v205, v45, v113
	ds_bpermute_b32 v206, v45, v114
	ds_bpermute_b32 v207, v45, v115
	ds_bpermute_b32 v208, v45, v116
	ds_bpermute_b32 v209, v45, v117
	ds_bpermute_b32 v210, v45, v118
	ds_bpermute_b32 v211, v45, v119
	ds_bpermute_b32 v212, v45, v120
	ds_bpermute_b32 v213, v45, v121
	ds_bpermute_b32 v214, v45, v122
	ds_bpermute_b32 v215, v45, v123
	s_waitcnt lgkmcnt(12)
	v_mfma_f32_16x16x32_bf16 v[4:7], v[220:223], v[216:219], v[4:7]
	v_mfma_f32_16x16x32_bf16 v[0:3], v[224:227], v[216:219], v[0:3]
	global_load_dwordx4 v[100:103], v[28:29], off offset:896
	global_load_dwordx4 v[104:107], v[30:31], off offset:896
	global_load_dwordx4 v[108:111], v[32:33], off offset:896
	s_waitcnt vmcnt(27)
	s_waitcnt lgkmcnt(3)
	ds_bpermute_b32 v216, v45, v124
	ds_bpermute_b32 v217, v45, v125
	ds_bpermute_b32 v218, v45, v126
	ds_bpermute_b32 v219, v45, v127
	ds_bpermute_b32 v220, v45, v128
	ds_bpermute_b32 v221, v45, v129
	ds_bpermute_b32 v222, v45, v130
	ds_bpermute_b32 v223, v45, v131
	ds_bpermute_b32 v224, v45, v132
	ds_bpermute_b32 v225, v45, v133
	ds_bpermute_b32 v226, v45, v134
	ds_bpermute_b32 v227, v45, v135
	s_waitcnt lgkmcnt(12)
	v_mfma_f32_16x16x32_bf16 v[4:7], v[208:211], v[204:207], v[4:7]
	v_mfma_f32_16x16x32_bf16 v[0:3], v[212:215], v[204:207], v[0:3]
	global_load_dwordx4 v[112:115], v[28:29], off offset:960
	global_load_dwordx4 v[116:119], v[30:31], off offset:960
	global_load_dwordx4 v[120:123], v[32:33], off offset:960
	s_waitcnt vmcnt(27)
	s_waitcnt lgkmcnt(3)
	ds_bpermute_b32 v204, v45, v136
	ds_bpermute_b32 v205, v45, v137
	ds_bpermute_b32 v206, v45, v138
	ds_bpermute_b32 v207, v45, v139
	ds_bpermute_b32 v208, v45, v140
	ds_bpermute_b32 v209, v45, v141
	ds_bpermute_b32 v210, v45, v142
	ds_bpermute_b32 v211, v45, v143
	ds_bpermute_b32 v212, v45, v144
	ds_bpermute_b32 v213, v45, v145
	ds_bpermute_b32 v214, v45, v146
	ds_bpermute_b32 v215, v45, v147
	s_waitcnt lgkmcnt(12)
	v_mfma_f32_16x16x32_bf16 v[4:7], v[220:223], v[216:219], v[4:7]
	v_mfma_f32_16x16x32_bf16 v[0:3], v[224:227], v[216:219], v[0:3]
	global_load_dwordx4 v[124:127], v[34:35], off
	global_load_dwordx4 v[128:131], v[36:37], off
	global_load_dwordx4 v[132:135], v[38:39], off
	s_waitcnt vmcnt(27)
	s_waitcnt lgkmcnt(3)
	ds_bpermute_b32 v216, v45, v148
	ds_bpermute_b32 v217, v45, v149
	ds_bpermute_b32 v218, v45, v150
	ds_bpermute_b32 v219, v45, v151
	ds_bpermute_b32 v220, v45, v152
	ds_bpermute_b32 v221, v45, v153
	ds_bpermute_b32 v222, v45, v154
	ds_bpermute_b32 v223, v45, v155
	ds_bpermute_b32 v224, v45, v156
	ds_bpermute_b32 v225, v45, v157
	ds_bpermute_b32 v226, v45, v158
	ds_bpermute_b32 v227, v45, v159
	s_waitcnt lgkmcnt(12)
	v_mfma_f32_16x16x32_bf16 v[4:7], v[208:211], v[204:207], v[4:7]
	v_mfma_f32_16x16x32_bf16 v[0:3], v[212:215], v[204:207], v[0:3]
	global_load_dwordx4 v[136:139], v[34:35], off offset:64
	global_load_dwordx4 v[140:143], v[36:37], off offset:64
	global_load_dwordx4 v[144:147], v[38:39], off offset:64
	s_waitcnt vmcnt(27)
	s_waitcnt lgkmcnt(3)
	ds_bpermute_b32 v204, v45, v160
	ds_bpermute_b32 v205, v45, v161
	ds_bpermute_b32 v206, v45, v162
	ds_bpermute_b32 v207, v45, v163
	ds_bpermute_b32 v208, v45, v164
	ds_bpermute_b32 v209, v45, v165
	ds_bpermute_b32 v210, v45, v166
	ds_bpermute_b32 v211, v45, v167
	ds_bpermute_b32 v212, v45, v168
	ds_bpermute_b32 v213, v45, v169
	ds_bpermute_b32 v214, v45, v170
	ds_bpermute_b32 v215, v45, v171
	s_waitcnt lgkmcnt(12)
	v_mfma_f32_16x16x32_bf16 v[4:7], v[220:223], v[216:219], v[4:7]
	v_mfma_f32_16x16x32_bf16 v[0:3], v[224:227], v[216:219], v[0:3]
	global_load_dwordx4 v[148:151], v[34:35], off offset:128
	global_load_dwordx4 v[152:155], v[36:37], off offset:128
	global_load_dwordx4 v[156:159], v[38:39], off offset:128
	s_waitcnt vmcnt(27)
	s_waitcnt lgkmcnt(3)
	ds_bpermute_b32 v216, v45, v172
	ds_bpermute_b32 v217, v45, v173
	ds_bpermute_b32 v218, v45, v174
	ds_bpermute_b32 v219, v45, v175
	ds_bpermute_b32 v220, v45, v176
	ds_bpermute_b32 v221, v45, v177
	ds_bpermute_b32 v222, v45, v178
	ds_bpermute_b32 v223, v45, v179
	ds_bpermute_b32 v224, v45, v180
	ds_bpermute_b32 v225, v45, v181
	ds_bpermute_b32 v226, v45, v182
	ds_bpermute_b32 v227, v45, v183
	s_waitcnt lgkmcnt(12)
	v_mfma_f32_16x16x32_bf16 v[4:7], v[208:211], v[204:207], v[4:7]
	v_mfma_f32_16x16x32_bf16 v[0:3], v[212:215], v[204:207], v[0:3]
	global_load_dwordx4 v[160:163], v[34:35], off offset:192
	global_load_dwordx4 v[164:167], v[36:37], off offset:192
	global_load_dwordx4 v[168:171], v[38:39], off offset:192
	s_waitcnt vmcnt(27)
	s_waitcnt lgkmcnt(3)
	ds_bpermute_b32 v204, v45, v184
	ds_bpermute_b32 v205, v45, v185
	ds_bpermute_b32 v206, v45, v186
	ds_bpermute_b32 v207, v45, v187
	ds_bpermute_b32 v208, v45, v188
	ds_bpermute_b32 v209, v45, v189
	ds_bpermute_b32 v210, v45, v190
	ds_bpermute_b32 v211, v45, v191
	ds_bpermute_b32 v212, v45, v192
	ds_bpermute_b32 v213, v45, v193
	ds_bpermute_b32 v214, v45, v194
	ds_bpermute_b32 v215, v45, v195
	s_waitcnt lgkmcnt(12)
	v_mfma_f32_16x16x32_bf16 v[4:7], v[220:223], v[216:219], v[4:7]
	v_mfma_f32_16x16x32_bf16 v[0:3], v[224:227], v[216:219], v[0:3]
	global_load_dwordx4 v[172:175], v[34:35], off offset:256
	global_load_dwordx4 v[176:179], v[36:37], off offset:256
	global_load_dwordx4 v[180:183], v[38:39], off offset:256
	s_waitcnt vmcnt(27)
; DEVI f32x4 mfma16(bf16x8 a, bf16x8 b, f32x4 c) { return __builtin_amdgcn_mfma_f32_16x16x32_bf16(a, b, c, 0, 0, 0); }
; DEVI void mini_kloop(const bf16_t* __restrict__ arow, const bf16_t* __restrict__ b0, const bf16_t* __restrict__ b1, const int K, f32x4 (&acc)[2]) {
; #pragma unroll 8
;     for (int k0 = 0; k0 < K; k0 += 32) {
;         const bf16x8 af = *(const bf16x8*)(arow + k0), w0 = *(const bf16x8*)(b0 + k0), w1 = *(const bf16x8*)(b1 + k0);
;         acc[0] = mfma16(w0, af, acc[0]); acc[1] = mfma16(w1, af, acc[1]);
;     }
; }
; DEVI void mini_mix_tile(const Params& p, const int t) {
;     ...
;     f32x4 aa[2] = {(f32x4){0.f, 0.f, 0.f, 0.f}, (f32x4){0.f, 0.f, 0.f, 0.f}}, ab[2] = {(f32x4){0.f, 0.f, 0.f, 0.f}, (f32x4){0.f, 0.f, 0.f, 0.f}};
;     mini_kloop(OA + (size_t)tok * 512 + 8 * g, WAT + (size_t)(colw + l15) * 512 + 8 * g, WAT + (size_t)(colw + 16 + l15) * 512 + 8 * g, 512, aa);
;     mini_kloop(OB + (size_t)tok * 512 + 8 * g, WBT + (size_t)(colw + l15) * 512 + 8 * g, WBT + (size_t)(colw + 16 + l15) * 512 + 8 * g, 512, ab);
	s_waitcnt lgkmcnt(3)
	ds_bpermute_b32 v216, v45, v64
	ds_bpermute_b32 v217, v45, v65
	ds_bpermute_b32 v218, v45, v66
	ds_bpermute_b32 v219, v45, v67
	ds_bpermute_b32 v220, v45, v68
	ds_bpermute_b32 v221, v45, v69
	ds_bpermute_b32 v222, v45, v70
	ds_bpermute_b32 v223, v45, v71
	ds_bpermute_b32 v224, v45, v72
	ds_bpermute_b32 v225, v45, v73
	ds_bpermute_b32 v226, v45, v74
	ds_bpermute_b32 v227, v45, v75
	s_waitcnt lgkmcnt(12)
	v_mfma_f32_16x16x32_bf16 v[4:7], v[208:211], v[204:207], v[4:7]
	v_mfma_f32_16x16x32_bf16 v[0:3], v[212:215], v[204:207], v[0:3]
	global_load_dwordx4 v[184:187], v[34:35], off offset:320
	global_load_dwordx4 v[188:191], v[36:37], off offset:320
	global_load_dwordx4 v[192:195], v[38:39], off offset:320
	s_waitcnt vmcnt(27)
	s_waitcnt lgkmcnt(3)
	ds_bpermute_b32 v204, v45, v76
	ds_bpermute_b32 v205, v45, v77
	ds_bpermute_b32 v206, v45, v78
	ds_bpermute_b32 v207, v45, v79
	ds_bpermute_b32 v208, v45, v80
	ds_bpermute_b32 v209, v45, v81
	ds_bpermute_b32 v210, v45, v82
	ds_bpermute_b32 v211, v45, v83
	ds_bpermute_b32 v212, v45, v84
	ds_bpermute_b32 v213, v45, v85
	ds_bpermute_b32 v214, v45, v86
	ds_bpermute_b32 v215, v45, v87
	s_waitcnt lgkmcnt(12)
	v_mfma_f32_16x16x32_bf16 v[4:7], v[220:223], v[216:219], v[4:7]
	v_mfma_f32_16x16x32_bf16 v[0:3], v[224:227], v[216:219], v[0:3]
	global_load_dwordx4 v[64:67], v[34:35], off offset:384
	global_load_dwordx4 v[68:71], v[36:37], off offset:384
	global_load_dwordx4 v[72:75], v[38:39], off offset:384
	s_waitcnt vmcnt(27)
	s_waitcnt lgkmcnt(3)
	ds_bpermute_b32 v216, v45, v88
	ds_bpermute_b32 v217, v45, v89
	ds_bpermute_b32 v218, v45, v90
	ds_bpermute_b32 v219, v45, v91
	ds_bpermute_b32 v220, v45, v92
	ds_bpermute_b32 v221, v45, v93
	ds_bpermute_b32 v222, v45, v94
	ds_bpermute_b32 v223, v45, v95
	ds_bpermute_b32 v224, v45, v96
	ds_bpermute_b32 v225, v45, v97
	ds_bpermute_b32 v226, v45, v98
	ds_bpermute_b32 v227, v45, v99
	s_waitcnt lgkmcnt(12)
	v_mfma_f32_16x16x32_bf16 v[4:7], v[208:211], v[204:207], v[4:7]
	v_mfma_f32_16x16x32_bf16 v[0:3], v[212:215], v[204:207], v[0:3]
	global_load_dwordx4 v[76:79], v[34:35], off offset:448
	global_load_dwordx4 v[80:83], v[36:37], off offset:448
	global_load_dwordx4 v[84:87], v[38:39], off offset:448
	s_waitcnt vmcnt(27)
	s_waitcnt lgkmcnt(3)
	ds_bpermute_b32 v204, v45, v100
	ds_bpermute_b32 v205, v45, v101
	ds_bpermute_b32 v206, v45, v102
	ds_bpermute_b32 v207, v45, v103
	ds_bpermute_b32 v208, v45, v104
	ds_bpermute_b32 v209, v45, v105
	ds_bpermute_b32 v210, v45, v106
	ds_bpermute_b32 v211, v45, v107
	ds_bpermute_b32 v212, v45, v108
	ds_bpermute_b32 v213, v45, v109
	ds_bpermute_b32 v214, v45, v110
	ds_bpermute_b32 v215, v45, v111
	s_waitcnt lgkmcnt(12)
	v_mfma_f32_16x16x32_bf16 v[4:7], v[220:223], v[216:219], v[4:7]
	v_mfma_f32_16x16x32_bf16 v[0:3], v[224:227], v[216:219], v[0:3]
	global_load_dwordx4 v[88:91], v[34:35], off offset:512
	global_load_dwordx4 v[92:95], v[36:37], off offset:512
	global_load_dwordx4 v[96:99], v[38:39], off offset:512
	s_waitcnt vmcnt(27)
	s_waitcnt lgkmcnt(3)
	ds_bpermute_b32 v216, v45, v112
	ds_bpermute_b32 v217, v45, v113
	ds_bpermute_b32 v218, v45, v114
	ds_bpermute_b32 v219, v45, v115
	ds_bpermute_b32 v220, v45, v116
	ds_bpermute_b32 v221, v45, v117
	ds_bpermute_b32 v222, v45, v118
	ds_bpermute_b32 v223, v45, v119
	ds_bpermute_b32 v224, v45, v120
	ds_bpermute_b32 v225, v45, v121
	ds_bpermute_b32 v226, v45, v122
	ds_bpermute_b32 v227, v45, v123
	s_waitcnt lgkmcnt(12)
	v_mfma_f32_16x16x32_bf16 v[4:7], v[208:211], v[204:207], v[4:7]
	v_mfma_f32_16x16x32_bf16 v[0:3], v[212:215], v[204:207], v[0:3]
	global_load_dwordx4 v[100:103], v[34:35], off offset:576
	global_load_dwordx4 v[104:107], v[36:37], off offset:576
	global_load_dwordx4 v[108:111], v[38:39], off offset:576
	s_waitcnt vmcnt(27)
	s_waitcnt lgkmcnt(3)
	ds_bpermute_b32 v204, v45, v124
	ds_bpermute_b32 v205, v45, v125
	ds_bpermute_b32 v206, v45, v126
	ds_bpermute_b32 v207, v45, v127
	ds_bpermute_b32 v208, v45, v128
	ds_bpermute_b32 v209, v45, v129
	ds_bpermute_b32 v210, v45, v130
	ds_bpermute_b32 v211, v45, v131
	ds_bpermute_b32 v212, v45, v132
	ds_bpermute_b32 v213, v45, v133
	ds_bpermute_b32 v214, v45, v134
	ds_bpermute_b32 v215, v45, v135
	s_waitcnt lgkmcnt(12)
	v_mfma_f32_16x16x32_bf16 v[4:7], v[220:223], v[216:219], v[4:7]
	v_mfma_f32_16x16x32_bf16 v[0:3], v[224:227], v[216:219], v[0:3]
	global_load_dwordx4 v[112:115], v[34:35], off offset:640
	global_load_dwordx4 v[116:119], v[36:37], off offset:640
	global_load_dwordx4 v[120:123], v[38:39], off offset:640
	s_waitcnt vmcnt(27)
	s_waitcnt lgkmcnt(3)
	ds_bpermute_b32 v216, v45, v136
	ds_bpermute_b32 v217, v45, v137
	ds_bpermute_b32 v218, v45, v138
	ds_bpermute_b32 v219, v45, v139
	ds_bpermute_b32 v220, v45, v140
	ds_bpermute_b32 v221, v45, v141
	ds_bpermute_b32 v222, v45, v142
	ds_bpermute_b32 v223, v45, v143
	ds_bpermute_b32 v224, v45, v144
	ds_bpermute_b32 v225, v45, v145
	ds_bpermute_b32 v226, v45, v146
	ds_bpermute_b32 v227, v45, v147
	s_waitcnt lgkmcnt(12)
	v_mfma_f32_16x16x32_bf16 v[12:15], v[208:211], v[204:207], v[12:15]
	v_mfma_f32_16x16x32_bf16 v[8:11], v[212:215], v[204:207], v[8:11]
	global_load_dwordx4 v[124:127], v[34:35], off offset:704
	global_load_dwordx4 v[128:131], v[36:37], off offset:704
	global_load_dwordx4 v[132:135], v[38:39], off offset:704
	s_waitcnt vmcnt(27)
	s_waitcnt lgkmcnt(3)
	ds_bpermute_b32 v204, v45, v148
	ds_bpermute_b32 v205, v45, v149
	ds_bpermute_b32 v206, v45, v150
	ds_bpermute_b32 v207, v45, v151
	ds_bpermute_b32 v208, v45, v152
	ds_bpermute_b32 v209, v45, v153
	ds_bpermute_b32 v210, v45, v154
	ds_bpermute_b32 v211, v45, v155
	ds_bpermute_b32 v212, v45, v156
	ds_bpermute_b32 v213, v45, v157
	ds_bpermute_b32 v214, v45, v158
	ds_bpermute_b32 v215, v45, v159
	s_waitcnt lgkmcnt(12)
; DEVI f32x4 mfma16(bf16x8 a, bf16x8 b, f32x4 c) { return __builtin_amdgcn_mfma_f32_16x16x32_bf16(a, b, c, 0, 0, 0); }
; DEVI void mini_kloop(const bf16_t* __restrict__ arow, const bf16_t* __restrict__ b0, const bf16_t* __restrict__ b1, const int K, f32x4 (&acc)[2]) {
; #pragma unroll 8
;     for (int k0 = 0; k0 < K; k0 += 32) {
;         const bf16x8 af = *(const bf16x8*)(arow + k0), w0 = *(const bf16x8*)(b0 + k0), w1 = *(const bf16x8*)(b1 + k0);
;         acc[0] = mfma16(w0, af, acc[0]); acc[1] = mfma16(w1, af, acc[1]);
;     }
	v_mfma_f32_16x16x32_bf16 v[12:15], v[220:223], v[216:219], v[12:15]
	v_mfma_f32_16x16x32_bf16 v[8:11], v[224:227], v[216:219], v[8:11]
	global_load_dwordx4 v[136:139], v[34:35], off offset:768
	global_load_dwordx4 v[140:143], v[36:37], off offset:768
	global_load_dwordx4 v[144:147], v[38:39], off offset:768
	s_waitcnt vmcnt(27)
	s_waitcnt lgkmcnt(3)
	ds_bpermute_b32 v216, v45, v160
	ds_bpermute_b32 v217, v45, v161
	ds_bpermute_b32 v218, v45, v162
	ds_bpermute_b32 v219, v45, v163
	ds_bpermute_b32 v220, v45, v164
	ds_bpermute_b32 v221, v45, v165
	ds_bpermute_b32 v222, v45, v166
	ds_bpermute_b32 v223, v45, v167
	ds_bpermute_b32 v224, v45, v168
	ds_bpermute_b32 v225, v45, v169
	ds_bpermute_b32 v226, v45, v170
	ds_bpermute_b32 v227, v45, v171
	s_waitcnt lgkmcnt(12)
	v_mfma_f32_16x16x32_bf16 v[12:15], v[208:211], v[204:207], v[12:15]
	v_mfma_f32_16x16x32_bf16 v[8:11], v[212:215], v[204:207], v[8:11]
	global_load_dwordx4 v[148:151], v[34:35], off offset:832
	global_load_dwordx4 v[152:155], v[36:37], off offset:832
	global_load_dwordx4 v[156:159], v[38:39], off offset:832
	s_waitcnt vmcnt(27)
	s_waitcnt lgkmcnt(3)
	ds_bpermute_b32 v204, v45, v172
	ds_bpermute_b32 v205, v45, v173
	ds_bpermute_b32 v206, v45, v174
	ds_bpermute_b32 v207, v45, v175
	ds_bpermute_b32 v208, v45, v176
	ds_bpermute_b32 v209, v45, v177
	ds_bpermute_b32 v210, v45, v178
	ds_bpermute_b32 v211, v45, v179
	ds_bpermute_b32 v212, v45, v180
	ds_bpermute_b32 v213, v45, v181
	ds_bpermute_b32 v214, v45, v182
	ds_bpermute_b32 v215, v45, v183
	s_waitcnt lgkmcnt(12)
	v_mfma_f32_16x16x32_bf16 v[12:15], v[220:223], v[216:219], v[12:15]
	v_mfma_f32_16x16x32_bf16 v[8:11], v[224:227], v[216:219], v[8:11]
	global_load_dwordx4 v[160:163], v[34:35], off offset:896
	global_load_dwordx4 v[164:167], v[36:37], off offset:896
	global_load_dwordx4 v[168:171], v[38:39], off offset:896
	s_waitcnt vmcnt(27)
	s_waitcnt lgkmcnt(3)
	ds_bpermute_b32 v216, v45, v184
	ds_bpermute_b32 v217, v45, v185
	ds_bpermute_b32 v218, v45, v186
	ds_bpermute_b32 v219, v45, v187
	ds_bpermute_b32 v220, v45, v188
	ds_bpermute_b32 v221, v45, v189
	ds_bpermute_b32 v222, v45, v190
	ds_bpermute_b32 v223, v45, v191
	ds_bpermute_b32 v224, v45, v192
	ds_bpermute_b32 v225, v45, v193
	ds_bpermute_b32 v226, v45, v194
	ds_bpermute_b32 v227, v45, v195
	s_waitcnt lgkmcnt(12)
	v_mfma_f32_16x16x32_bf16 v[12:15], v[208:211], v[204:207], v[12:15]
	v_mfma_f32_16x16x32_bf16 v[8:11], v[212:215], v[204:207], v[8:11]
	global_load_dwordx4 v[172:175], v[34:35], off offset:960
	global_load_dwordx4 v[176:179], v[36:37], off offset:960
	global_load_dwordx4 v[180:183], v[38:39], off offset:960
	s_waitcnt vmcnt(27)
	s_waitcnt lgkmcnt(3)
	ds_bpermute_b32 v204, v45, v64
	ds_bpermute_b32 v205, v45, v65
	ds_bpermute_b32 v206, v45, v66
	ds_bpermute_b32 v207, v45, v67
	ds_bpermute_b32 v208, v45, v68
	ds_bpermute_b32 v209, v45, v69
	ds_bpermute_b32 v210, v45, v70
	ds_bpermute_b32 v211, v45, v71
	ds_bpermute_b32 v212, v45, v72
	ds_bpermute_b32 v213, v45, v73
	ds_bpermute_b32 v214, v45, v74
	ds_bpermute_b32 v215, v45, v75
	s_waitcnt lgkmcnt(12)
	v_mfma_f32_16x16x32_bf16 v[12:15], v[220:223], v[216:219], v[12:15]
	v_mfma_f32_16x16x32_bf16 v[8:11], v[224:227], v[216:219], v[8:11]
	s_waitcnt vmcnt(24)
	s_waitcnt lgkmcnt(3)
	ds_bpermute_b32 v216, v45, v76
	ds_bpermute_b32 v217, v45, v77
	ds_bpermute_b32 v218, v45, v78
	ds_bpermute_b32 v219, v45, v79
	ds_bpermute_b32 v220, v45, v80
	ds_bpermute_b32 v221, v45, v81
	ds_bpermute_b32 v222, v45, v82
	ds_bpermute_b32 v223, v45, v83
	ds_bpermute_b32 v224, v45, v84
	ds_bpermute_b32 v225, v45, v85
	ds_bpermute_b32 v226, v45, v86
	ds_bpermute_b32 v227, v45, v87
	s_waitcnt lgkmcnt(12)
	v_mfma_f32_16x16x32_bf16 v[12:15], v[208:211], v[204:207], v[12:15]
	v_mfma_f32_16x16x32_bf16 v[8:11], v[212:215], v[204:207], v[8:11]
	s_waitcnt vmcnt(21)
	s_waitcnt lgkmcnt(3)
	ds_bpermute_b32 v204, v45, v88
	ds_bpermute_b32 v205, v45, v89
	ds_bpermute_b32 v206, v45, v90
	ds_bpermute_b32 v207, v45, v91
	ds_bpermute_b32 v208, v45, v92
	ds_bpermute_b32 v209, v45, v93
	ds_bpermute_b32 v210, v45, v94
	ds_bpermute_b32 v211, v45, v95
	ds_bpermute_b32 v212, v45, v96
	ds_bpermute_b32 v213, v45, v97
	ds_bpermute_b32 v214, v45, v98
	ds_bpermute_b32 v215, v45, v99
	s_waitcnt lgkmcnt(12)
	v_mfma_f32_16x16x32_bf16 v[12:15], v[220:223], v[216:219], v[12:15]
	v_mfma_f32_16x16x32_bf16 v[8:11], v[224:227], v[216:219], v[8:11]
	s_waitcnt vmcnt(18)
	s_waitcnt lgkmcnt(3)
	ds_bpermute_b32 v216, v45, v100
	ds_bpermute_b32 v217, v45, v101
	ds_bpermute_b32 v218, v45, v102
	ds_bpermute_b32 v219, v45, v103
	ds_bpermute_b32 v220, v45, v104
	ds_bpermute_b32 v221, v45, v105
	ds_bpermute_b32 v222, v45, v106
	ds_bpermute_b32 v223, v45, v107
	ds_bpermute_b32 v224, v45, v108
	ds_bpermute_b32 v225, v45, v109
	ds_bpermute_b32 v226, v45, v110
	ds_bpermute_b32 v227, v45, v111
	s_waitcnt lgkmcnt(12)
	v_mfma_f32_16x16x32_bf16 v[12:15], v[208:211], v[204:207], v[12:15]
	v_mfma_f32_16x16x32_bf16 v[8:11], v[212:215], v[204:207], v[8:11]
	s_waitcnt vmcnt(15)
	s_waitcnt lgkmcnt(3)
	ds_bpermute_b32 v204, v45, v112
	ds_bpermute_b32 v205, v45, v113
	ds_bpermute_b32 v206, v45, v114
	ds_bpermute_b32 v207, v45, v115
	ds_bpermute_b32 v208, v45, v116
	ds_bpermute_b32 v209, v45, v117
	ds_bpermute_b32 v210, v45, v118
	ds_bpermute_b32 v211, v45, v119
	ds_bpermute_b32 v212, v45, v120
	ds_bpermute_b32 v213, v45, v121
	ds_bpermute_b32 v214, v45, v122
	ds_bpermute_b32 v215, v45, v123
	s_waitcnt lgkmcnt(12)
	v_mfma_f32_16x16x32_bf16 v[12:15], v[220:223], v[216:219], v[12:15]
	v_mfma_f32_16x16x32_bf16 v[8:11], v[224:227], v[216:219], v[8:11]
	s_waitcnt vmcnt(12)
	s_waitcnt lgkmcnt(3)
; DEVI unsigned pk_bf16(float lo, float hi) { const f32x2_t v = {lo, hi}; const bf16x2_t b = __builtin_convertvector(v, bf16x2_t); return __builtin_bit_cast(unsigned, b); }
; DEVI float bf_lo(unsigned u) { return __uint_as_float(u << 16); }
; DEVI float bf_hi(unsigned u) { return __uint_as_float(u & 0xffff0000u); }
; DEVI f32x4 mfma16(bf16x8 a, bf16x8 b, f32x4 c) { return __builtin_amdgcn_mfma_f32_16x16x32_bf16(a, b, c, 0, 0, 0); }
; DEVI void mini_kloop(const bf16_t* __restrict__ arow, const bf16_t* __restrict__ b0, const bf16_t* __restrict__ b1, const int K, f32x4 (&acc)[2]) {
; #pragma unroll 8
;     for (int k0 = 0; k0 < K; k0 += 32) {
;         const bf16x8 af = *(const bf16x8*)(arow + k0), w0 = *(const bf16x8*)(b0 + k0), w1 = *(const bf16x8*)(b1 + k0);
;         acc[0] = mfma16(w0, af, acc[0]); acc[1] = mfma16(w1, af, acc[1]);
;     }
; DEVI void mini_mix_tile(const Params& p, const int t) {
;     ...
;     const bf16_t* G = (const bf16_t*)p.out; bf16_t* MX = (bf16_t*)(p.ws + W_XN);
; #pragma unroll
;     for (int tt = 0; tt < 2; ++tt) {
;         const int col = colw + 16 * tt + 4 * g;
;         const u32x2 ga = *(const u32x2*)(G + (size_t)tok * 2048 + col), gb = *(const u32x2*)(G + (size_t)tok * 2048 + 1024 + col);
;         f32x4 m;
;         m[0] = aa[tt][0] * bf_lo(ga.x) + ab[tt][0] * bf_lo(gb.x); m[1] = aa[tt][1] * bf_hi(ga.x) + ab[tt][1] * bf_hi(gb.x);
;         m[2] = aa[tt][2] * bf_lo(ga.y) + ab[tt][2] * bf_lo(gb.y); m[3] = aa[tt][3] * bf_hi(ga.y) + ab[tt][3] * bf_hi(gb.y);
;         u32x2 o; o.x = pk_bf16(m[0], m[1]); o.y = pk_bf16(m[2], m[3]);
;         *(u32x2*)(MX + (size_t)tok * 1024 + col) = o;
;     }
	ds_bpermute_b32 v216, v45, v124
	ds_bpermute_b32 v217, v45, v125
	ds_bpermute_b32 v218, v45, v126
	ds_bpermute_b32 v219, v45, v127
	ds_bpermute_b32 v220, v45, v128
	ds_bpermute_b32 v221, v45, v129
	ds_bpermute_b32 v222, v45, v130
	ds_bpermute_b32 v223, v45, v131
	ds_bpermute_b32 v224, v45, v132
	ds_bpermute_b32 v225, v45, v133
	ds_bpermute_b32 v226, v45, v134
	ds_bpermute_b32 v227, v45, v135
	s_waitcnt lgkmcnt(12)
	v_mfma_f32_16x16x32_bf16 v[12:15], v[208:211], v[204:207], v[12:15]
	v_mfma_f32_16x16x32_bf16 v[8:11], v[212:215], v[204:207], v[8:11]
	s_waitcnt vmcnt(9)
	s_waitcnt lgkmcnt(3)
	ds_bpermute_b32 v204, v45, v136
	ds_bpermute_b32 v205, v45, v137
	ds_bpermute_b32 v206, v45, v138
	ds_bpermute_b32 v207, v45, v139
	ds_bpermute_b32 v208, v45, v140
	ds_bpermute_b32 v209, v45, v141
	ds_bpermute_b32 v210, v45, v142
	ds_bpermute_b32 v211, v45, v143
	ds_bpermute_b32 v212, v45, v144
	ds_bpermute_b32 v213, v45, v145
	ds_bpermute_b32 v214, v45, v146
	ds_bpermute_b32 v215, v45, v147
	s_waitcnt lgkmcnt(12)
	v_mfma_f32_16x16x32_bf16 v[12:15], v[220:223], v[216:219], v[12:15]
	v_mfma_f32_16x16x32_bf16 v[8:11], v[224:227], v[216:219], v[8:11]
	s_waitcnt vmcnt(6)
	s_waitcnt lgkmcnt(3)
	ds_bpermute_b32 v216, v45, v148
	ds_bpermute_b32 v217, v45, v149
	ds_bpermute_b32 v218, v45, v150
	ds_bpermute_b32 v219, v45, v151
	ds_bpermute_b32 v220, v45, v152
	ds_bpermute_b32 v221, v45, v153
	ds_bpermute_b32 v222, v45, v154
	ds_bpermute_b32 v223, v45, v155
	ds_bpermute_b32 v224, v45, v156
	ds_bpermute_b32 v225, v45, v157
	ds_bpermute_b32 v226, v45, v158
	ds_bpermute_b32 v227, v45, v159
	s_waitcnt lgkmcnt(12)
	v_mfma_f32_16x16x32_bf16 v[12:15], v[208:211], v[204:207], v[12:15]
	v_mfma_f32_16x16x32_bf16 v[8:11], v[212:215], v[204:207], v[8:11]
	s_waitcnt vmcnt(3)
	s_waitcnt lgkmcnt(3)
	ds_bpermute_b32 v204, v45, v160
	ds_bpermute_b32 v205, v45, v161
	ds_bpermute_b32 v206, v45, v162
	ds_bpermute_b32 v207, v45, v163
	ds_bpermute_b32 v208, v45, v164
	ds_bpermute_b32 v209, v45, v165
	ds_bpermute_b32 v210, v45, v166
	ds_bpermute_b32 v211, v45, v167
	ds_bpermute_b32 v212, v45, v168
	ds_bpermute_b32 v213, v45, v169
	ds_bpermute_b32 v214, v45, v170
	ds_bpermute_b32 v215, v45, v171
	s_waitcnt lgkmcnt(12)
	v_mfma_f32_16x16x32_bf16 v[12:15], v[220:223], v[216:219], v[12:15]
	v_mfma_f32_16x16x32_bf16 v[8:11], v[224:227], v[216:219], v[8:11]
	s_waitcnt vmcnt(0)
	s_waitcnt lgkmcnt(3)
	ds_bpermute_b32 v216, v45, v172
	ds_bpermute_b32 v217, v45, v173
	ds_bpermute_b32 v218, v45, v174
	ds_bpermute_b32 v219, v45, v175
	ds_bpermute_b32 v220, v45, v176
	ds_bpermute_b32 v221, v45, v177
	ds_bpermute_b32 v222, v45, v178
	ds_bpermute_b32 v223, v45, v179
	ds_bpermute_b32 v224, v45, v180
	ds_bpermute_b32 v225, v45, v181
	ds_bpermute_b32 v226, v45, v182
	ds_bpermute_b32 v227, v45, v183
	s_waitcnt lgkmcnt(12)
	v_mfma_f32_16x16x32_bf16 v[12:15], v[208:211], v[204:207], v[12:15]
	v_mfma_f32_16x16x32_bf16 v[8:11], v[212:215], v[204:207], v[8:11]
	s_waitcnt lgkmcnt(0)
	v_mfma_f32_16x16x32_bf16 v[12:15], v[220:223], v[216:219], v[12:15]
	v_mfma_f32_16x16x32_bf16 v[8:11], v[224:227], v[216:219], v[8:11]
	s_lshl_b32 s3, s7, 2
	s_andn2_b32 s3, s3, 63
	s_add_i32 s3, s3, 0x8000
	v_or3_b32 v18, v25, s3, v24
	s_lshl_b32 s3, s7, 6
	s_and_b32 s3, s3, 0x3c0
	v_and_b32_e32 v16, 3, v27
	v_add_u32_e32 v20, s3, v26
	v_ashrrev_i32_e32 v19, 31, v18
	v_lshl_or_b32 v20, v16, 2, v20
	v_readlane_b32 s12, v234, 24
	v_lshlrev_b64 v[22:23], 12, v[18:19]
	v_readlane_b32 s26, v234, 38
	v_readlane_b32 s27, v234, 39
	v_ashrrev_i32_e32 v21, 31, v20
	v_lshlrev_b64 v[20:21], 1, v[20:21]
	v_lshl_add_u64 v[22:23], s[26:27], 0, v[22:23]
	v_lshl_add_u64 v[22:23], v[22:23], 0, v[20:21]
	global_load_dwordx2 v[24:25], v[22:23], off
	global_load_dwordx2 v[26:27], v[22:23], off offset:2048
	v_lshlrev_b64 v[18:19], 11, v[18:19]
	v_lshl_add_u64 v[18:19], s[88:89], 0, v[18:19]
	v_lshl_add_u64 v[18:19], v[18:19], 0, v[20:21]
	s_add_i32 s7, s7, s97
	s_add_i32 s2, s2, s4
	s_add_i32 s5, s5, s6
	s_cmpk_gt_i32 s7, 0xff
	v_readlane_b32 s13, v234, 25
	v_readlane_b32 s14, v234, 26
	v_readlane_b32 s15, v234, 27
	v_readlane_b32 s16, v234, 28
	v_readlane_b32 s17, v234, 29
	v_readlane_b32 s18, v234, 30
	v_readlane_b32 s19, v234, 31
	v_readlane_b32 s20, v234, 32
	v_readlane_b32 s21, v234, 33
	v_readlane_b32 s22, v234, 34
	v_readlane_b32 s23, v234, 35
	v_readlane_b32 s24, v234, 36
	v_readlane_b32 s25, v234, 37
	s_waitcnt vmcnt(1)
	v_lshlrev_b32_e32 v20, 16, v24
	s_waitcnt vmcnt(0)
	v_lshlrev_b32_e32 v28, 16, v26
	v_and_b32_e32 v29, 0xffff0000, v26
	v_lshlrev_b32_e32 v26, 16, v27
	v_and_b32_e32 v27, 0xffff0000, v27
	v_and_b32_e32 v21, 0xffff0000, v24
	v_lshlrev_b32_e32 v24, 16, v25
	v_and_b32_e32 v25, 0xffff0000, v25
	v_pk_mul_f32 v[12:13], v[12:13], v[28:29]
	v_pk_mul_f32 v[14:15], v[14:15], v[26:27]
	v_pk_fma_f32 v[4:5], v[4:5], v[20:21], v[12:13]
	v_pk_fma_f32 v[6:7], v[6:7], v[24:25], v[14:15]
	v_cvt_pk_bf16_f32 v4, v4, v5
	v_cvt_pk_bf16_f32 v5, v6, v7
	global_store_dwordx2 v[18:19], v[4:5], off
	global_load_dwordx2 v[4:5], v[22:23], off offset:32
	s_nop 0
	global_load_dwordx2 v[6:7], v[22:23], off offset:2080
	s_waitcnt vmcnt(1)
	v_lshlrev_b32_e32 v12, 16, v4
	s_waitcnt vmcnt(0)
	v_lshlrev_b32_e32 v14, 16, v6
	v_and_b32_e32 v15, 0xffff0000, v6
	v_lshlrev_b32_e32 v6, 16, v7
	v_and_b32_e32 v7, 0xffff0000, v7
	v_and_b32_e32 v13, 0xffff0000, v4
	v_lshlrev_b32_e32 v4, 16, v5
	v_and_b32_e32 v5, 0xffff0000, v5
	v_pk_mul_f32 v[8:9], v[8:9], v[14:15]
	v_pk_mul_f32 v[6:7], v[10:11], v[6:7]
	v_pk_fma_f32 v[0:1], v[0:1], v[12:13], v[8:9]
	v_pk_fma_f32 v[2:3], v[2:3], v[4:5], v[6:7]
	v_cvt_pk_bf16_f32 v0, v0, v1
	v_cvt_pk_bf16_f32 v1, v2, v3
	global_store_dwordx2 v[18:19], v[0:1], off offset:32
	s_cbranch_scc0 .LBB0_994

; DEVI f32x4 mfma16(bf16x8 a, bf16x8 b, f32x4 c) { return __builtin_amdgcn_mfma_f32_16x16x32_bf16(a, b, c, 0, 0, 0); }
; DEVI void mini_kloop(const bf16_t* __restrict__ arow, const bf16_t* __restrict__ b0, const bf16_t* __restrict__ b1, const int K, f32x4 (&acc)[2]) {
; #pragma unroll 8
;     for (int k0 = 0; k0 < K; k0 += 32) {
;         const bf16x8 af = *(const bf16x8*)(arow + k0), w0 = *(const bf16x8*)(b0 + k0), w1 = *(const bf16x8*)(b1 + k0);
;         acc[0] = mfma16(w0, af, acc[0]); acc[1] = mfma16(w1, af, acc[1]);
;     }
; DEVI void mini_y_tile(const Params& p, const int t) {
;     int tid = threadIdx.x; asm volatile("" : "+v"(tid));
;     const int lane = tid & 63, w = tid >> 6, l15 = lane & 15, g = lane >> 4;
;     const int tok = NTP + 64 * (t >> 4) + 16 * (w & 3) + l15, colw = 64 * (t & 15) + 32 * (w >> 2);
;     const bf16_t* MX = (const bf16_t*)(p.ws + W_XN); const bf16_t* WOT = (const bf16_t*)(p.ws + W_WOT);
;     f32x4 acc[2] = {(f32x4){0.f, 0.f, 0.f, 0.f}, (f32x4){0.f, 0.f, 0.f, 0.f}};
;     mini_kloop(MX + (size_t)tok * 1024 + 8 * g, WOT + (size_t)(colw + l15) * 1024 + 8 * g, WOT + (size_t)(colw + 16 + l15) * 1024 + 8 * g, 1024, acc);
.LBB0_1208:
	v_lshl_add_u64 v[20:21], v[12:13], 0, v[8:9]
	v_lshl_add_u64 v[22:23], v[14:15], 0, v[8:9]
	v_lshl_add_u64 v[24:25], v[10:11], 0, v[8:9]
	v_add_co_u32_e32 v22, vcc, s9, v22
	s_nop 1
	v_addc_co_u32_e32 v23, vcc, 0, v23, vcc
	v_add_co_u32_e32 v24, vcc, s9, v24
	s_nop 1
	v_addc_co_u32_e32 v25, vcc, 0, v25, vcc
	v_and_b32_e32 v40, 63, v203
	v_and_b32_e32 v41, 3, v40
	v_lshrrev_b32_e32 v42, 4, v40
	v_bfe_u32 v43, v40, 2, 2
	v_lshl_add_u32 v44, v42, 2, v43
	v_lshl_add_u32 v44, v41, 4, v44
	v_lshlrev_b32_e32 v44, 2, v44
	v_lshlrev_b32_e32 v45, 4, v43
	v_lshl_add_u32 v45, v41, 2, v45
	v_add_u32_e32 v45, v45, v42
	v_lshlrev_b32_e32 v45, 2, v45
	ds_bpermute_b32 v20, v44, v20
	ds_bpermute_b32 v21, v44, v21
	ds_bpermute_b32 v22, v44, v22
	ds_bpermute_b32 v23, v44, v23
	ds_bpermute_b32 v24, v44, v24
	ds_bpermute_b32 v25, v44, v25
	s_waitcnt lgkmcnt(0)
	global_load_dwordx4 v[64:67], v[20:21], off
	global_load_dwordx4 v[68:71], v[22:23], off
	global_load_dwordx4 v[72:75], v[24:25], off
	global_load_dwordx4 v[76:79], v[20:21], off offset:64
	global_load_dwordx4 v[80:83], v[22:23], off offset:64
	global_load_dwordx4 v[84:87], v[24:25], off offset:64
	global_load_dwordx4 v[88:91], v[20:21], off offset:128
	global_load_dwordx4 v[92:95], v[22:23], off offset:128
	global_load_dwordx4 v[96:99], v[24:25], off offset:128
	global_load_dwordx4 v[100:103], v[20:21], off offset:192
	global_load_dwordx4 v[104:107], v[22:23], off offset:192
	global_load_dwordx4 v[108:111], v[24:25], off offset:192
	global_load_dwordx4 v[112:115], v[20:21], off offset:256
	global_load_dwordx4 v[116:119], v[22:23], off offset:256
	global_load_dwordx4 v[120:123], v[24:25], off offset:256
	global_load_dwordx4 v[124:127], v[20:21], off offset:320
	global_load_dwordx4 v[128:131], v[22:23], off offset:320
	global_load_dwordx4 v[132:135], v[24:25], off offset:320
	global_load_dwordx4 v[136:139], v[20:21], off offset:384
	global_load_dwordx4 v[140:143], v[22:23], off offset:384
	global_load_dwordx4 v[144:147], v[24:25], off offset:384
	global_load_dwordx4 v[148:151], v[20:21], off offset:448
	global_load_dwordx4 v[152:155], v[22:23], off offset:448
	global_load_dwordx4 v[156:159], v[24:25], off offset:448
	global_load_dwordx4 v[160:163], v[20:21], off offset:512
	global_load_dwordx4 v[164:167], v[22:23], off offset:512
	global_load_dwordx4 v[168:171], v[24:25], off offset:512
	global_load_dwordx4 v[172:175], v[20:21], off offset:576
	global_load_dwordx4 v[176:179], v[22:23], off offset:576
	global_load_dwordx4 v[180:183], v[24:25], off offset:576
	global_load_dwordx4 v[184:187], v[20:21], off offset:640
	global_load_dwordx4 v[188:191], v[22:23], off offset:640
	global_load_dwordx4 v[192:195], v[24:25], off offset:640
	s_waitcnt vmcnt(30)
	ds_bpermute_b32 v204, v45, v64
	ds_bpermute_b32 v205, v45, v65
	ds_bpermute_b32 v206, v45, v66
	ds_bpermute_b32 v207, v45, v67
	ds_bpermute_b32 v208, v45, v68
	ds_bpermute_b32 v209, v45, v69
	ds_bpermute_b32 v210, v45, v70
	ds_bpermute_b32 v211, v45, v71
	ds_bpermute_b32 v212, v45, v72
	ds_bpermute_b32 v213, v45, v73
	ds_bpermute_b32 v214, v45, v74
	ds_bpermute_b32 v215, v45, v75
	s_waitcnt vmcnt(27)
	s_waitcnt lgkmcnt(3)
	ds_bpermute_b32 v216, v45, v76
	ds_bpermute_b32 v217, v45, v77
	ds_bpermute_b32 v218, v45, v78
	ds_bpermute_b32 v219, v45, v79
	ds_bpermute_b32 v220, v45, v80
	ds_bpermute_b32 v221, v45, v81
	ds_bpermute_b32 v222, v45, v82
	ds_bpermute_b32 v223, v45, v83
	ds_bpermute_b32 v224, v45, v84
	ds_bpermute_b32 v225, v45, v85
	ds_bpermute_b32 v226, v45, v86
	ds_bpermute_b32 v227, v45, v87
	s_waitcnt lgkmcnt(12)
	v_mfma_f32_16x16x32_bf16 v[4:7], v[208:211], v[204:207], v[4:7]
	v_mfma_f32_16x16x32_bf16 v[0:3], v[212:215], v[204:207], v[0:3]
	global_load_dwordx4 v[64:67], v[20:21], off offset:704
	global_load_dwordx4 v[68:71], v[22:23], off offset:704
	global_load_dwordx4 v[72:75], v[24:25], off offset:704
	s_waitcnt vmcnt(27)
	s_waitcnt lgkmcnt(3)
	ds_bpermute_b32 v204, v45, v88
	ds_bpermute_b32 v205, v45, v89
	ds_bpermute_b32 v206, v45, v90
	ds_bpermute_b32 v207, v45, v91
	ds_bpermute_b32 v208, v45, v92
	ds_bpermute_b32 v209, v45, v93
	ds_bpermute_b32 v210, v45, v94
	ds_bpermute_b32 v211, v45, v95
	ds_bpermute_b32 v212, v45, v96
	ds_bpermute_b32 v213, v45, v97
	ds_bpermute_b32 v214, v45, v98
	ds_bpermute_b32 v215, v45, v99
	s_waitcnt lgkmcnt(12)
	v_mfma_f32_16x16x32_bf16 v[4:7], v[220:223], v[216:219], v[4:7]
	v_mfma_f32_16x16x32_bf16 v[0:3], v[224:227], v[216:219], v[0:3]
	global_load_dwordx4 v[76:79], v[20:21], off offset:768
	global_load_dwordx4 v[80:83], v[22:23], off offset:768
	global_load_dwordx4 v[84:87], v[24:25], off offset:768
	s_waitcnt vmcnt(27)
	s_waitcnt lgkmcnt(3)
	ds_bpermute_b32 v216, v45, v100
	ds_bpermute_b32 v217, v45, v101
	ds_bpermute_b32 v218, v45, v102
	ds_bpermute_b32 v219, v45, v103
	ds_bpermute_b32 v220, v45, v104
	ds_bpermute_b32 v221, v45, v105
	ds_bpermute_b32 v222, v45, v106
	ds_bpermute_b32 v223, v45, v107
	ds_bpermute_b32 v224, v45, v108
	ds_bpermute_b32 v225, v45, v109
	ds_bpermute_b32 v226, v45, v110
	ds_bpermute_b32 v227, v45, v111
	s_waitcnt lgkmcnt(12)
	v_mfma_f32_16x16x32_bf16 v[4:7], v[208:211], v[204:207], v[4:7]
	v_mfma_f32_16x16x32_bf16 v[0:3], v[212:215], v[204:207], v[0:3]
	global_load_dwordx4 v[88:91], v[20:21], off offset:832
	global_load_dwordx4 v[92:95], v[22:23], off offset:832
	global_load_dwordx4 v[96:99], v[24:25], off offset:832
	s_waitcnt vmcnt(27)
	s_waitcnt lgkmcnt(3)
	ds_bpermute_b32 v204, v45, v112
	ds_bpermute_b32 v205, v45, v113
	ds_bpermute_b32 v206, v45, v114
	ds_bpermute_b32 v207, v45, v115
	ds_bpermute_b32 v208, v45, v116
	ds_bpermute_b32 v209, v45, v117
	ds_bpermute_b32 v210, v45, v118
	ds_bpermute_b32 v211, v45, v119
	ds_bpermute_b32 v212, v45, v120
	ds_bpermute_b32 v213, v45, v121
	ds_bpermute_b32 v214, v45, v122
	ds_bpermute_b32 v215, v45, v123
	s_waitcnt lgkmcnt(12)
; DEVI f32x4 mfma16(bf16x8 a, bf16x8 b, f32x4 c) { return __builtin_amdgcn_mfma_f32_16x16x32_bf16(a, b, c, 0, 0, 0); }
; DEVI void mini_kloop(const bf16_t* __restrict__ arow, const bf16_t* __restrict__ b0, const bf16_t* __restrict__ b1, const int K, f32x4 (&acc)[2]) {
; #pragma unroll 8
;     for (int k0 = 0; k0 < K; k0 += 32) {
;         const bf16x8 af = *(const bf16x8*)(arow + k0), w0 = *(const bf16x8*)(b0 + k0), w1 = *(const bf16x8*)(b1 + k0);
;         acc[0] = mfma16(w0, af, acc[0]); acc[1] = mfma16(w1, af, acc[1]);
;     }
	v_mfma_f32_16x16x32_bf16 v[4:7], v[220:223], v[216:219], v[4:7]
	v_mfma_f32_16x16x32_bf16 v[0:3], v[224:227], v[216:219], v[0:3]
	global_load_dwordx4 v[100:103], v[20:21], off offset:896
	global_load_dwordx4 v[104:107], v[22:23], off offset:896
	global_load_dwordx4 v[108:111], v[24:25], off offset:896
	s_waitcnt vmcnt(27)
	s_waitcnt lgkmcnt(3)
	ds_bpermute_b32 v216, v45, v124
	ds_bpermute_b32 v217, v45, v125
	ds_bpermute_b32 v218, v45, v126
	ds_bpermute_b32 v219, v45, v127
	ds_bpermute_b32 v220, v45, v128
	ds_bpermute_b32 v221, v45, v129
	ds_bpermute_b32 v222, v45, v130
	ds_bpermute_b32 v223, v45, v131
	ds_bpermute_b32 v224, v45, v132
	ds_bpermute_b32 v225, v45, v133
	ds_bpermute_b32 v226, v45, v134
	ds_bpermute_b32 v227, v45, v135
	s_waitcnt lgkmcnt(12)
	v_mfma_f32_16x16x32_bf16 v[4:7], v[208:211], v[204:207], v[4:7]
	v_mfma_f32_16x16x32_bf16 v[0:3], v[212:215], v[204:207], v[0:3]
	global_load_dwordx4 v[112:115], v[20:21], off offset:960
	global_load_dwordx4 v[116:119], v[22:23], off offset:960
	global_load_dwordx4 v[120:123], v[24:25], off offset:960
	s_waitcnt vmcnt(27)
	s_waitcnt lgkmcnt(3)
	ds_bpermute_b32 v204, v45, v136
	ds_bpermute_b32 v205, v45, v137
	ds_bpermute_b32 v206, v45, v138
	ds_bpermute_b32 v207, v45, v139
	ds_bpermute_b32 v208, v45, v140
	ds_bpermute_b32 v209, v45, v141
	ds_bpermute_b32 v210, v45, v142
	ds_bpermute_b32 v211, v45, v143
	ds_bpermute_b32 v212, v45, v144
	ds_bpermute_b32 v213, v45, v145
	ds_bpermute_b32 v214, v45, v146
	ds_bpermute_b32 v215, v45, v147
	s_waitcnt lgkmcnt(12)
	v_mfma_f32_16x16x32_bf16 v[4:7], v[220:223], v[216:219], v[4:7]
	v_mfma_f32_16x16x32_bf16 v[0:3], v[224:227], v[216:219], v[0:3]
	global_load_dwordx4 v[124:127], v[20:21], off offset:1024
	global_load_dwordx4 v[128:131], v[22:23], off offset:1024
	global_load_dwordx4 v[132:135], v[24:25], off offset:1024
	s_waitcnt vmcnt(27)
	s_waitcnt lgkmcnt(3)
	ds_bpermute_b32 v216, v45, v148
	ds_bpermute_b32 v217, v45, v149
	ds_bpermute_b32 v218, v45, v150
	ds_bpermute_b32 v219, v45, v151
	ds_bpermute_b32 v220, v45, v152
	ds_bpermute_b32 v221, v45, v153
	ds_bpermute_b32 v222, v45, v154
	ds_bpermute_b32 v223, v45, v155
	ds_bpermute_b32 v224, v45, v156
	ds_bpermute_b32 v225, v45, v157
	ds_bpermute_b32 v226, v45, v158
	ds_bpermute_b32 v227, v45, v159
	s_waitcnt lgkmcnt(12)
	v_mfma_f32_16x16x32_bf16 v[4:7], v[208:211], v[204:207], v[4:7]
	v_mfma_f32_16x16x32_bf16 v[0:3], v[212:215], v[204:207], v[0:3]
	global_load_dwordx4 v[136:139], v[20:21], off offset:1088
	global_load_dwordx4 v[140:143], v[22:23], off offset:1088
	global_load_dwordx4 v[144:147], v[24:25], off offset:1088
	s_waitcnt vmcnt(27)
	s_waitcnt lgkmcnt(3)
	ds_bpermute_b32 v204, v45, v160
	ds_bpermute_b32 v205, v45, v161
	ds_bpermute_b32 v206, v45, v162
	ds_bpermute_b32 v207, v45, v163
	ds_bpermute_b32 v208, v45, v164
	ds_bpermute_b32 v209, v45, v165
	ds_bpermute_b32 v210, v45, v166
	ds_bpermute_b32 v211, v45, v167
	ds_bpermute_b32 v212, v45, v168
	ds_bpermute_b32 v213, v45, v169
	ds_bpermute_b32 v214, v45, v170
	ds_bpermute_b32 v215, v45, v171
	s_waitcnt lgkmcnt(12)
	v_mfma_f32_16x16x32_bf16 v[4:7], v[220:223], v[216:219], v[4:7]
	v_mfma_f32_16x16x32_bf16 v[0:3], v[224:227], v[216:219], v[0:3]
	global_load_dwordx4 v[148:151], v[20:21], off offset:1152
	global_load_dwordx4 v[152:155], v[22:23], off offset:1152
	global_load_dwordx4 v[156:159], v[24:25], off offset:1152
	s_waitcnt vmcnt(27)
	s_waitcnt lgkmcnt(3)
	ds_bpermute_b32 v216, v45, v172
	ds_bpermute_b32 v217, v45, v173
	ds_bpermute_b32 v218, v45, v174
	ds_bpermute_b32 v219, v45, v175
	ds_bpermute_b32 v220, v45, v176
	ds_bpermute_b32 v221, v45, v177
	ds_bpermute_b32 v222, v45, v178
	ds_bpermute_b32 v223, v45, v179
	ds_bpermute_b32 v224, v45, v180
	ds_bpermute_b32 v225, v45, v181
	ds_bpermute_b32 v226, v45, v182
	ds_bpermute_b32 v227, v45, v183
	s_waitcnt lgkmcnt(12)
	v_mfma_f32_16x16x32_bf16 v[4:7], v[208:211], v[204:207], v[4:7]
	v_mfma_f32_16x16x32_bf16 v[0:3], v[212:215], v[204:207], v[0:3]
	global_load_dwordx4 v[160:163], v[20:21], off offset:1216
	global_load_dwordx4 v[164:167], v[22:23], off offset:1216
	global_load_dwordx4 v[168:171], v[24:25], off offset:1216
	s_waitcnt vmcnt(27)
	s_waitcnt lgkmcnt(3)
	ds_bpermute_b32 v204, v45, v184
	ds_bpermute_b32 v205, v45, v185
	ds_bpermute_b32 v206, v45, v186
	ds_bpermute_b32 v207, v45, v187
	ds_bpermute_b32 v208, v45, v188
	ds_bpermute_b32 v209, v45, v189
	ds_bpermute_b32 v210, v45, v190
	ds_bpermute_b32 v211, v45, v191
	ds_bpermute_b32 v212, v45, v192
	ds_bpermute_b32 v213, v45, v193
	ds_bpermute_b32 v214, v45, v194
	ds_bpermute_b32 v215, v45, v195
	s_waitcnt lgkmcnt(12)
	v_mfma_f32_16x16x32_bf16 v[4:7], v[220:223], v[216:219], v[4:7]
	v_mfma_f32_16x16x32_bf16 v[0:3], v[224:227], v[216:219], v[0:3]
	global_load_dwordx4 v[172:175], v[20:21], off offset:1280
	global_load_dwordx4 v[176:179], v[22:23], off offset:1280
	global_load_dwordx4 v[180:183], v[24:25], off offset:1280
	s_waitcnt vmcnt(27)
	s_waitcnt lgkmcnt(3)
	ds_bpermute_b32 v216, v45, v64
	ds_bpermute_b32 v217, v45, v65
	ds_bpermute_b32 v218, v45, v66
	ds_bpermute_b32 v219, v45, v67
	ds_bpermute_b32 v220, v45, v68
	ds_bpermute_b32 v221, v45, v69
	ds_bpermute_b32 v222, v45, v70
	ds_bpermute_b32 v223, v45, v71
	ds_bpermute_b32 v224, v45, v72
	ds_bpermute_b32 v225, v45, v73
	ds_bpermute_b32 v226, v45, v74
	ds_bpermute_b32 v227, v45, v75
	s_waitcnt lgkmcnt(12)
	v_mfma_f32_16x16x32_bf16 v[4:7], v[208:211], v[204:207], v[4:7]
	v_mfma_f32_16x16x32_bf16 v[0:3], v[212:215], v[204:207], v[0:3]
	global_load_dwordx4 v[184:187], v[20:21], off offset:1344
	global_load_dwordx4 v[188:191], v[22:23], off offset:1344
	global_load_dwordx4 v[192:195], v[24:25], off offset:1344
	s_waitcnt vmcnt(27)
; DEVI f32x4 mfma16(bf16x8 a, bf16x8 b, f32x4 c) { return __builtin_amdgcn_mfma_f32_16x16x32_bf16(a, b, c, 0, 0, 0); }
; DEVI void mini_kloop(const bf16_t* __restrict__ arow, const bf16_t* __restrict__ b0, const bf16_t* __restrict__ b1, const int K, f32x4 (&acc)[2]) {
; #pragma unroll 8
;     for (int k0 = 0; k0 < K; k0 += 32) {
;         const bf16x8 af = *(const bf16x8*)(arow + k0), w0 = *(const bf16x8*)(b0 + k0), w1 = *(const bf16x8*)(b1 + k0);
;         acc[0] = mfma16(w0, af, acc[0]); acc[1] = mfma16(w1, af, acc[1]);
;     }
	s_waitcnt lgkmcnt(3)
	ds_bpermute_b32 v204, v45, v76
	ds_bpermute_b32 v205, v45, v77
	ds_bpermute_b32 v206, v45, v78
	ds_bpermute_b32 v207, v45, v79
	ds_bpermute_b32 v208, v45, v80
	ds_bpermute_b32 v209, v45, v81
	ds_bpermute_b32 v210, v45, v82
	ds_bpermute_b32 v211, v45, v83
	ds_bpermute_b32 v212, v45, v84
	ds_bpermute_b32 v213, v45, v85
	ds_bpermute_b32 v214, v45, v86
	ds_bpermute_b32 v215, v45, v87
	s_waitcnt lgkmcnt(12)
	v_mfma_f32_16x16x32_bf16 v[4:7], v[220:223], v[216:219], v[4:7]
	v_mfma_f32_16x16x32_bf16 v[0:3], v[224:227], v[216:219], v[0:3]
	global_load_dwordx4 v[64:67], v[20:21], off offset:1408
	global_load_dwordx4 v[68:71], v[22:23], off offset:1408
	global_load_dwordx4 v[72:75], v[24:25], off offset:1408
	s_waitcnt vmcnt(27)
	s_waitcnt lgkmcnt(3)
	ds_bpermute_b32 v216, v45, v88
	ds_bpermute_b32 v217, v45, v89
	ds_bpermute_b32 v218, v45, v90
	ds_bpermute_b32 v219, v45, v91
	ds_bpermute_b32 v220, v45, v92
	ds_bpermute_b32 v221, v45, v93
	ds_bpermute_b32 v222, v45, v94
	ds_bpermute_b32 v223, v45, v95
	ds_bpermute_b32 v224, v45, v96
	ds_bpermute_b32 v225, v45, v97
	ds_bpermute_b32 v226, v45, v98
	ds_bpermute_b32 v227, v45, v99
	s_waitcnt lgkmcnt(12)
	v_mfma_f32_16x16x32_bf16 v[4:7], v[208:211], v[204:207], v[4:7]
	v_mfma_f32_16x16x32_bf16 v[0:3], v[212:215], v[204:207], v[0:3]
	global_load_dwordx4 v[76:79], v[20:21], off offset:1472
	global_load_dwordx4 v[80:83], v[22:23], off offset:1472
	global_load_dwordx4 v[84:87], v[24:25], off offset:1472
	s_waitcnt vmcnt(27)
	s_waitcnt lgkmcnt(3)
	ds_bpermute_b32 v204, v45, v100
	ds_bpermute_b32 v205, v45, v101
	ds_bpermute_b32 v206, v45, v102
	ds_bpermute_b32 v207, v45, v103
	ds_bpermute_b32 v208, v45, v104
	ds_bpermute_b32 v209, v45, v105
	ds_bpermute_b32 v210, v45, v106
	ds_bpermute_b32 v211, v45, v107
	ds_bpermute_b32 v212, v45, v108
	ds_bpermute_b32 v213, v45, v109
	ds_bpermute_b32 v214, v45, v110
	ds_bpermute_b32 v215, v45, v111
	s_waitcnt lgkmcnt(12)
	v_mfma_f32_16x16x32_bf16 v[4:7], v[220:223], v[216:219], v[4:7]
	v_mfma_f32_16x16x32_bf16 v[0:3], v[224:227], v[216:219], v[0:3]
	global_load_dwordx4 v[88:91], v[20:21], off offset:1536
	global_load_dwordx4 v[92:95], v[22:23], off offset:1536
	global_load_dwordx4 v[96:99], v[24:25], off offset:1536
	s_waitcnt vmcnt(27)
	s_waitcnt lgkmcnt(3)
	ds_bpermute_b32 v216, v45, v112
	ds_bpermute_b32 v217, v45, v113
	ds_bpermute_b32 v218, v45, v114
	ds_bpermute_b32 v219, v45, v115
	ds_bpermute_b32 v220, v45, v116
	ds_bpermute_b32 v221, v45, v117
	ds_bpermute_b32 v222, v45, v118
	ds_bpermute_b32 v223, v45, v119
	ds_bpermute_b32 v224, v45, v120
	ds_bpermute_b32 v225, v45, v121
	ds_bpermute_b32 v226, v45, v122
	ds_bpermute_b32 v227, v45, v123
	s_waitcnt lgkmcnt(12)
	v_mfma_f32_16x16x32_bf16 v[4:7], v[208:211], v[204:207], v[4:7]
	v_mfma_f32_16x16x32_bf16 v[0:3], v[212:215], v[204:207], v[0:3]
	global_load_dwordx4 v[100:103], v[20:21], off offset:1600
	global_load_dwordx4 v[104:107], v[22:23], off offset:1600
	global_load_dwordx4 v[108:111], v[24:25], off offset:1600
	s_waitcnt vmcnt(27)
	s_waitcnt lgkmcnt(3)
	ds_bpermute_b32 v204, v45, v124
	ds_bpermute_b32 v205, v45, v125
	ds_bpermute_b32 v206, v45, v126
	ds_bpermute_b32 v207, v45, v127
	ds_bpermute_b32 v208, v45, v128
	ds_bpermute_b32 v209, v45, v129
	ds_bpermute_b32 v210, v45, v130
	ds_bpermute_b32 v211, v45, v131
	ds_bpermute_b32 v212, v45, v132
	ds_bpermute_b32 v213, v45, v133
	ds_bpermute_b32 v214, v45, v134
	ds_bpermute_b32 v215, v45, v135
	s_waitcnt lgkmcnt(12)
	v_mfma_f32_16x16x32_bf16 v[4:7], v[220:223], v[216:219], v[4:7]
	v_mfma_f32_16x16x32_bf16 v[0:3], v[224:227], v[216:219], v[0:3]
	global_load_dwordx4 v[112:115], v[20:21], off offset:1664
	global_load_dwordx4 v[116:119], v[22:23], off offset:1664
	global_load_dwordx4 v[120:123], v[24:25], off offset:1664
	s_waitcnt vmcnt(27)
	s_waitcnt lgkmcnt(3)
	ds_bpermute_b32 v216, v45, v136
	ds_bpermute_b32 v217, v45, v137
	ds_bpermute_b32 v218, v45, v138
	ds_bpermute_b32 v219, v45, v139
	ds_bpermute_b32 v220, v45, v140
	ds_bpermute_b32 v221, v45, v141
	ds_bpermute_b32 v222, v45, v142
	ds_bpermute_b32 v223, v45, v143
	ds_bpermute_b32 v224, v45, v144
	ds_bpermute_b32 v225, v45, v145
	ds_bpermute_b32 v226, v45, v146
	ds_bpermute_b32 v227, v45, v147
	s_waitcnt lgkmcnt(12)
	v_mfma_f32_16x16x32_bf16 v[4:7], v[208:211], v[204:207], v[4:7]
	v_mfma_f32_16x16x32_bf16 v[0:3], v[212:215], v[204:207], v[0:3]
	global_load_dwordx4 v[124:127], v[20:21], off offset:1728
	global_load_dwordx4 v[128:131], v[22:23], off offset:1728
	global_load_dwordx4 v[132:135], v[24:25], off offset:1728
	s_waitcnt vmcnt(27)
	s_waitcnt lgkmcnt(3)
	ds_bpermute_b32 v204, v45, v148
	ds_bpermute_b32 v205, v45, v149
	ds_bpermute_b32 v206, v45, v150
	ds_bpermute_b32 v207, v45, v151
	ds_bpermute_b32 v208, v45, v152
	ds_bpermute_b32 v209, v45, v153
	ds_bpermute_b32 v210, v45, v154
	ds_bpermute_b32 v211, v45, v155
	ds_bpermute_b32 v212, v45, v156
	ds_bpermute_b32 v213, v45, v157
	ds_bpermute_b32 v214, v45, v158
	ds_bpermute_b32 v215, v45, v159
	s_waitcnt lgkmcnt(12)
	v_mfma_f32_16x16x32_bf16 v[4:7], v[220:223], v[216:219], v[4:7]
	v_mfma_f32_16x16x32_bf16 v[0:3], v[224:227], v[216:219], v[0:3]
	global_load_dwordx4 v[136:139], v[20:21], off offset:1792
	global_load_dwordx4 v[140:143], v[22:23], off offset:1792
	global_load_dwordx4 v[144:147], v[24:25], off offset:1792
	s_waitcnt vmcnt(27)
	s_waitcnt lgkmcnt(3)
	ds_bpermute_b32 v216, v45, v160
	ds_bpermute_b32 v217, v45, v161
	ds_bpermute_b32 v218, v45, v162
	ds_bpermute_b32 v219, v45, v163
	ds_bpermute_b32 v220, v45, v164
	ds_bpermute_b32 v221, v45, v165
	ds_bpermute_b32 v222, v45, v166
	ds_bpermute_b32 v223, v45, v167
	ds_bpermute_b32 v224, v45, v168
	ds_bpermute_b32 v225, v45, v169
	ds_bpermute_b32 v226, v45, v170
	ds_bpermute_b32 v227, v45, v171
	s_waitcnt lgkmcnt(12)
; DEVI f32x4 mfma16(bf16x8 a, bf16x8 b, f32x4 c) { return __builtin_amdgcn_mfma_f32_16x16x32_bf16(a, b, c, 0, 0, 0); }
; DEVI void mini_kloop(const bf16_t* __restrict__ arow, const bf16_t* __restrict__ b0, const bf16_t* __restrict__ b1, const int K, f32x4 (&acc)[2]) {
; #pragma unroll 8
;     for (int k0 = 0; k0 < K; k0 += 32) {
;         const bf16x8 af = *(const bf16x8*)(arow + k0), w0 = *(const bf16x8*)(b0 + k0), w1 = *(const bf16x8*)(b1 + k0);
;         acc[0] = mfma16(w0, af, acc[0]); acc[1] = mfma16(w1, af, acc[1]);
;     }
	v_mfma_f32_16x16x32_bf16 v[4:7], v[208:211], v[204:207], v[4:7]
	v_mfma_f32_16x16x32_bf16 v[0:3], v[212:215], v[204:207], v[0:3]
	global_load_dwordx4 v[148:151], v[20:21], off offset:1856
	global_load_dwordx4 v[152:155], v[22:23], off offset:1856
	global_load_dwordx4 v[156:159], v[24:25], off offset:1856
	s_waitcnt vmcnt(27)
	s_waitcnt lgkmcnt(3)
	ds_bpermute_b32 v204, v45, v172
	ds_bpermute_b32 v205, v45, v173
	ds_bpermute_b32 v206, v45, v174
	ds_bpermute_b32 v207, v45, v175
	ds_bpermute_b32 v208, v45, v176
	ds_bpermute_b32 v209, v45, v177
	ds_bpermute_b32 v210, v45, v178
	ds_bpermute_b32 v211, v45, v179
	ds_bpermute_b32 v212, v45, v180
	ds_bpermute_b32 v213, v45, v181
	ds_bpermute_b32 v214, v45, v182
	ds_bpermute_b32 v215, v45, v183
	s_waitcnt lgkmcnt(12)
	v_mfma_f32_16x16x32_bf16 v[4:7], v[220:223], v[216:219], v[4:7]
	v_mfma_f32_16x16x32_bf16 v[0:3], v[224:227], v[216:219], v[0:3]
	global_load_dwordx4 v[160:163], v[20:21], off offset:1920
	global_load_dwordx4 v[164:167], v[22:23], off offset:1920
	global_load_dwordx4 v[168:171], v[24:25], off offset:1920
	s_waitcnt vmcnt(27)
	s_waitcnt lgkmcnt(3)
	ds_bpermute_b32 v216, v45, v184
	ds_bpermute_b32 v217, v45, v185
	ds_bpermute_b32 v218, v45, v186
	ds_bpermute_b32 v219, v45, v187
	ds_bpermute_b32 v220, v45, v188
	ds_bpermute_b32 v221, v45, v189
	ds_bpermute_b32 v222, v45, v190
	ds_bpermute_b32 v223, v45, v191
	ds_bpermute_b32 v224, v45, v192
	ds_bpermute_b32 v225, v45, v193
	ds_bpermute_b32 v226, v45, v194
	ds_bpermute_b32 v227, v45, v195
	s_waitcnt lgkmcnt(12)
	v_mfma_f32_16x16x32_bf16 v[4:7], v[208:211], v[204:207], v[4:7]
	v_mfma_f32_16x16x32_bf16 v[0:3], v[212:215], v[204:207], v[0:3]
	global_load_dwordx4 v[172:175], v[20:21], off offset:1984
	global_load_dwordx4 v[176:179], v[22:23], off offset:1984
	global_load_dwordx4 v[180:183], v[24:25], off offset:1984
	s_waitcnt vmcnt(27)
	s_waitcnt lgkmcnt(3)
	ds_bpermute_b32 v204, v45, v64
	ds_bpermute_b32 v205, v45, v65
	ds_bpermute_b32 v206, v45, v66
	ds_bpermute_b32 v207, v45, v67
	ds_bpermute_b32 v208, v45, v68
	ds_bpermute_b32 v209, v45, v69
	ds_bpermute_b32 v210, v45, v70
	ds_bpermute_b32 v211, v45, v71
	ds_bpermute_b32 v212, v45, v72
	ds_bpermute_b32 v213, v45, v73
	ds_bpermute_b32 v214, v45, v74
	ds_bpermute_b32 v215, v45, v75
	s_waitcnt lgkmcnt(12)
	v_mfma_f32_16x16x32_bf16 v[4:7], v[220:223], v[216:219], v[4:7]
	v_mfma_f32_16x16x32_bf16 v[0:3], v[224:227], v[216:219], v[0:3]
	s_waitcnt vmcnt(24)
	s_waitcnt lgkmcnt(3)
	ds_bpermute_b32 v216, v45, v76
	ds_bpermute_b32 v217, v45, v77
	ds_bpermute_b32 v218, v45, v78
	ds_bpermute_b32 v219, v45, v79
	ds_bpermute_b32 v220, v45, v80
	ds_bpermute_b32 v221, v45, v81
	ds_bpermute_b32 v222, v45, v82
	ds_bpermute_b32 v223, v45, v83
	ds_bpermute_b32 v224, v45, v84
	ds_bpermute_b32 v225, v45, v85
	ds_bpermute_b32 v226, v45, v86
	ds_bpermute_b32 v227, v45, v87
	s_waitcnt lgkmcnt(12)
	v_mfma_f32_16x16x32_bf16 v[4:7], v[208:211], v[204:207], v[4:7]
	v_mfma_f32_16x16x32_bf16 v[0:3], v[212:215], v[204:207], v[0:3]
	s_waitcnt vmcnt(21)
	s_waitcnt lgkmcnt(3)
	ds_bpermute_b32 v204, v45, v88
	ds_bpermute_b32 v205, v45, v89
	ds_bpermute_b32 v206, v45, v90
	ds_bpermute_b32 v207, v45, v91
	ds_bpermute_b32 v208, v45, v92
	ds_bpermute_b32 v209, v45, v93
	ds_bpermute_b32 v210, v45, v94
	ds_bpermute_b32 v211, v45, v95
	ds_bpermute_b32 v212, v45, v96
	ds_bpermute_b32 v213, v45, v97
	ds_bpermute_b32 v214, v45, v98
	ds_bpermute_b32 v215, v45, v99
	s_waitcnt lgkmcnt(12)
	v_mfma_f32_16x16x32_bf16 v[4:7], v[220:223], v[216:219], v[4:7]
	v_mfma_f32_16x16x32_bf16 v[0:3], v[224:227], v[216:219], v[0:3]
	s_waitcnt vmcnt(18)
	s_waitcnt lgkmcnt(3)
	ds_bpermute_b32 v216, v45, v100
	ds_bpermute_b32 v217, v45, v101
	ds_bpermute_b32 v218, v45, v102
	ds_bpermute_b32 v219, v45, v103
	ds_bpermute_b32 v220, v45, v104
	ds_bpermute_b32 v221, v45, v105
	ds_bpermute_b32 v222, v45, v106
	ds_bpermute_b32 v223, v45, v107
	ds_bpermute_b32 v224, v45, v108
	ds_bpermute_b32 v225, v45, v109
	ds_bpermute_b32 v226, v45, v110
	ds_bpermute_b32 v227, v45, v111
	s_waitcnt lgkmcnt(12)
	v_mfma_f32_16x16x32_bf16 v[4:7], v[208:211], v[204:207], v[4:7]
	v_mfma_f32_16x16x32_bf16 v[0:3], v[212:215], v[204:207], v[0:3]
	s_waitcnt vmcnt(15)
	s_waitcnt lgkmcnt(3)
	ds_bpermute_b32 v204, v45, v112
	ds_bpermute_b32 v205, v45, v113
	ds_bpermute_b32 v206, v45, v114
	ds_bpermute_b32 v207, v45, v115
	ds_bpermute_b32 v208, v45, v116
	ds_bpermute_b32 v209, v45, v117
	ds_bpermute_b32 v210, v45, v118
	ds_bpermute_b32 v211, v45, v119
	ds_bpermute_b32 v212, v45, v120
	ds_bpermute_b32 v213, v45, v121
	ds_bpermute_b32 v214, v45, v122
	ds_bpermute_b32 v215, v45, v123
	s_waitcnt lgkmcnt(12)
	v_mfma_f32_16x16x32_bf16 v[4:7], v[220:223], v[216:219], v[4:7]
	v_mfma_f32_16x16x32_bf16 v[0:3], v[224:227], v[216:219], v[0:3]
	s_waitcnt vmcnt(12)
	s_waitcnt lgkmcnt(3)
; DEVI f32x4 mfma16(bf16x8 a, bf16x8 b, f32x4 c) { return __builtin_amdgcn_mfma_f32_16x16x32_bf16(a, b, c, 0, 0, 0); }
; DEVI void mini_kloop(const bf16_t* __restrict__ arow, const bf16_t* __restrict__ b0, const bf16_t* __restrict__ b1, const int K, f32x4 (&acc)[2]) {
; #pragma unroll 8
;     for (int k0 = 0; k0 < K; k0 += 32) {
;         const bf16x8 af = *(const bf16x8*)(arow + k0), w0 = *(const bf16x8*)(b0 + k0), w1 = *(const bf16x8*)(b1 + k0);
;         acc[0] = mfma16(w0, af, acc[0]); acc[1] = mfma16(w1, af, acc[1]);
;     }
; DEVI void mini_y_tile(const Params& p, const int t) {
;     ...
;     const float* xr = p.x_s + (size_t)(tok - NTP) * 1024;
; #pragma unroll
;     for (int tt = 0; tt < 2; ++tt) {
;         const int col = colw + 16 * tt + 4 * g;
;         const f32x4 xv = *(const f32x4*)(xr + col);
;         *(f32x4*)(p.out + (size_t)tok * 1024 + col) = xv + acc[tt];
;     }
	ds_bpermute_b32 v216, v45, v124
	ds_bpermute_b32 v217, v45, v125
	ds_bpermute_b32 v218, v45, v126
	ds_bpermute_b32 v219, v45, v127
	ds_bpermute_b32 v220, v45, v128
	ds_bpermute_b32 v221, v45, v129
	ds_bpermute_b32 v222, v45, v130
	ds_bpermute_b32 v223, v45, v131
	ds_bpermute_b32 v224, v45, v132
	ds_bpermute_b32 v225, v45, v133
	ds_bpermute_b32 v226, v45, v134
	ds_bpermute_b32 v227, v45, v135
	s_waitcnt lgkmcnt(12)
	v_mfma_f32_16x16x32_bf16 v[4:7], v[208:211], v[204:207], v[4:7]
	v_mfma_f32_16x16x32_bf16 v[0:3], v[212:215], v[204:207], v[0:3]
	s_waitcnt vmcnt(9)
	s_waitcnt lgkmcnt(3)
	ds_bpermute_b32 v204, v45, v136
	ds_bpermute_b32 v205, v45, v137
	ds_bpermute_b32 v206, v45, v138
	ds_bpermute_b32 v207, v45, v139
	ds_bpermute_b32 v208, v45, v140
	ds_bpermute_b32 v209, v45, v141
	ds_bpermute_b32 v210, v45, v142
	ds_bpermute_b32 v211, v45, v143
	ds_bpermute_b32 v212, v45, v144
	ds_bpermute_b32 v213, v45, v145
	ds_bpermute_b32 v214, v45, v146
	ds_bpermute_b32 v215, v45, v147
	s_waitcnt lgkmcnt(12)
	v_mfma_f32_16x16x32_bf16 v[4:7], v[220:223], v[216:219], v[4:7]
	v_mfma_f32_16x16x32_bf16 v[0:3], v[224:227], v[216:219], v[0:3]
	s_waitcnt vmcnt(6)
	s_waitcnt lgkmcnt(3)
	ds_bpermute_b32 v216, v45, v148
	ds_bpermute_b32 v217, v45, v149
	ds_bpermute_b32 v218, v45, v150
	ds_bpermute_b32 v219, v45, v151
	ds_bpermute_b32 v220, v45, v152
	ds_bpermute_b32 v221, v45, v153
	ds_bpermute_b32 v222, v45, v154
	ds_bpermute_b32 v223, v45, v155
	ds_bpermute_b32 v224, v45, v156
	ds_bpermute_b32 v225, v45, v157
	ds_bpermute_b32 v226, v45, v158
	ds_bpermute_b32 v227, v45, v159
	s_waitcnt lgkmcnt(12)
	v_mfma_f32_16x16x32_bf16 v[4:7], v[208:211], v[204:207], v[4:7]
	v_mfma_f32_16x16x32_bf16 v[0:3], v[212:215], v[204:207], v[0:3]
	s_waitcnt vmcnt(3)
	s_waitcnt lgkmcnt(3)
	ds_bpermute_b32 v204, v45, v160
	ds_bpermute_b32 v205, v45, v161
	ds_bpermute_b32 v206, v45, v162
	ds_bpermute_b32 v207, v45, v163
	ds_bpermute_b32 v208, v45, v164
	ds_bpermute_b32 v209, v45, v165
	ds_bpermute_b32 v210, v45, v166
	ds_bpermute_b32 v211, v45, v167
	ds_bpermute_b32 v212, v45, v168
	ds_bpermute_b32 v213, v45, v169
	ds_bpermute_b32 v214, v45, v170
	ds_bpermute_b32 v215, v45, v171
	s_waitcnt lgkmcnt(12)
	v_mfma_f32_16x16x32_bf16 v[4:7], v[220:223], v[216:219], v[4:7]
	v_mfma_f32_16x16x32_bf16 v[0:3], v[224:227], v[216:219], v[0:3]
	s_waitcnt vmcnt(0)
	s_waitcnt lgkmcnt(3)
	ds_bpermute_b32 v216, v45, v172
	ds_bpermute_b32 v217, v45, v173
	ds_bpermute_b32 v218, v45, v174
	ds_bpermute_b32 v219, v45, v175
	ds_bpermute_b32 v220, v45, v176
	ds_bpermute_b32 v221, v45, v177
	ds_bpermute_b32 v222, v45, v178
	ds_bpermute_b32 v223, v45, v179
	ds_bpermute_b32 v224, v45, v180
	ds_bpermute_b32 v225, v45, v181
	ds_bpermute_b32 v226, v45, v182
	ds_bpermute_b32 v227, v45, v183
	s_waitcnt lgkmcnt(12)
	v_mfma_f32_16x16x32_bf16 v[4:7], v[208:211], v[204:207], v[4:7]
	v_mfma_f32_16x16x32_bf16 v[0:3], v[212:215], v[204:207], v[0:3]
	s_waitcnt lgkmcnt(0)
	v_mfma_f32_16x16x32_bf16 v[4:7], v[220:223], v[216:219], v[4:7]
	v_mfma_f32_16x16x32_bf16 v[0:3], v[224:227], v[216:219], v[0:3]
	s_lshl_b32 s3, s11, 2
	s_andn2_b32 s3, s3, 63
	s_add_i32 s3, s3, 0x8000
	v_or3_b32 v10, v17, s3, v16
	s_lshl_b32 s3, s11, 6
	s_and_b32 s3, s3, 0x3c0
	v_and_b32_e32 v8, 3, v19
	v_add_u32_e32 v12, s3, v18
	v_ashrrev_i32_e32 v11, 31, v10
	v_readlane_b32 s12, v234, 2
	v_lshl_or_b32 v12, v8, 2, v12
	v_lshlrev_b64 v[14:15], 12, v[10:11]
	v_readlane_b32 s14, v234, 4
	v_readlane_b32 s15, v234, 5
	v_ashrrev_i32_e32 v13, 31, v12
	v_lshlrev_b64 v[16:17], 2, v[12:13]
	v_lshl_add_u64 v[10:11], s[14:15], 0, v[14:15]
	v_lshl_add_u64 v[18:19], v[10:11], 0, v[16:17]
	v_add_co_u32_e32 v10, vcc, s10, v18
	v_readlane_b32 s13, v234, 3
	s_nop 0
	v_addc_co_u32_e32 v11, vcc, -1, v19, vcc
	global_load_dwordx4 v[10:13], v[10:11], off
	v_readlane_b32 s16, v234, 6
	v_readlane_b32 s17, v234, 7
	v_readlane_b32 s18, v234, 8
	v_readlane_b32 s19, v234, 9
	v_readlane_b32 s20, v234, 10
	v_readlane_b32 s21, v234, 11
	v_readlane_b32 s22, v234, 12
	v_readlane_b32 s23, v234, 13
	v_readlane_b32 s24, v234, 14
	v_readlane_b32 s25, v234, 15
	v_readlane_b32 s26, v234, 16
	v_readlane_b32 s27, v234, 17
	v_readlane_b32 s12, v234, 24
	v_readlane_b32 s26, v234, 38
	v_readlane_b32 s27, v234, 39
	s_add_i32 s11, s11, s97
	s_add_i32 s2, s2, s6
	v_lshl_add_u64 v[14:15], s[26:27], 0, v[14:15]
	v_lshl_add_u64 v[14:15], v[14:15], 0, v[16:17]
	v_lshl_add_u64 v[16:17], v[18:19], 0, s[4:5]
	s_add_i32 s7, s7, s8
	s_cmpk_gt_i32 s11, 0xff
	v_readlane_b32 s13, v234, 25
	v_readlane_b32 s14, v234, 26
	v_readlane_b32 s15, v234, 27
	v_readlane_b32 s16, v234, 28
	v_readlane_b32 s17, v234, 29
	v_readlane_b32 s18, v234, 30
	v_readlane_b32 s19, v234, 31
	v_readlane_b32 s20, v234, 32
	v_readlane_b32 s21, v234, 33
	v_readlane_b32 s22, v234, 34
	v_readlane_b32 s23, v234, 35
	v_readlane_b32 s24, v234, 36
	v_readlane_b32 s25, v234, 37
	s_waitcnt vmcnt(0)
	v_pk_add_f32 v[6:7], v[6:7], v[12:13]
	v_pk_add_f32 v[4:5], v[4:5], v[10:11]
	global_store_dwordx4 v[14:15], v[4:7], off
	global_load_dwordx4 v[4:7], v[16:17], off offset:64
	s_waitcnt vmcnt(0)
	v_pk_add_f32 v[2:3], v[2:3], v[6:7]
	v_pk_add_f32 v[0:1], v[0:1], v[4:5]
	global_store_dwordx4 v[14:15], v[0:3], off offset:64
	s_cbranch_scc0 .LBB0_1207
